# cv32 + sample-unit scan: the four per-step state loads hoisted and issued together (counted vmcnt(3) waits) instead of load-wait-store chains
# baseline (speedup 1.0000x reference)
.LBB0_661:
	s_or_b64 exec, exec, s[8:9]
	v_add_f32_e32 v41, -1.0, v95
	v_sub_f32_e32 v42, v41, v95
	v_add_f32_e32 v42, 1.0, v42
	v_sub_f32_e32 v41, v93, v41
	v_add_f32_e32 v41, v41, v42
	v_sub_u32_e32 v42, 0, v73
	v_ldexp_f32 v43, v95, v42
	v_ldexp_f32 v41, v41, v42
	v_add_f32_e32 v42, -1.0, v43
	v_add_f32_e32 v44, 1.0, v42
	v_sub_f32_e32 v44, v43, v44
	v_add_f32_e32 v44, v41, v44
	v_add_f32_e32 v45, v42, v44
	v_sub_f32_e32 v42, v42, v45
	v_add_f32_e32 v42, v44, v42
	v_add_f32_e32 v44, 1.0, v43
	v_add_f32_e32 v46, -1.0, v44
	v_sub_f32_e32 v43, v43, v46
	v_add_f32_e32 v41, v41, v43
	v_add_f32_e32 v43, v44, v41
	v_sub_f32_e32 v44, v44, v43
	v_add_f32_e32 v41, v41, v44
	v_rcp_f32_e32 v44, v43
	s_mov_b32 s8, 0x3f317218
	v_max_f32_e32 v40, v94, v94
	v_min_f32_e32 v40, 0, v40
	v_mul_f32_e32 v46, v45, v44
	v_mul_f32_e32 v47, v43, v46
	v_fma_f32 v48, v46, v43, -v47
	v_fmac_f32_e32 v48, v46, v41
	v_add_f32_e32 v49, v47, v48
	v_sub_f32_e32 v50, v45, v49
	v_sub_f32_e32 v45, v45, v50
	v_sub_f32_e32 v47, v49, v47
	v_sub_f32_e32 v45, v45, v49
	v_add_f32_e32 v42, v42, v45
	v_sub_f32_e32 v45, v47, v48
	v_add_f32_e32 v42, v45, v42
	v_add_f32_e32 v45, v50, v42
	v_mul_f32_e32 v47, v44, v45
	v_mul_f32_e32 v48, v43, v47
	v_fma_f32 v43, v47, v43, -v48
	v_fmac_f32_e32 v43, v47, v41
	v_sub_f32_e32 v41, v50, v45
	v_add_f32_e32 v41, v42, v41
	v_add_f32_e32 v42, v48, v43
	v_sub_f32_e32 v49, v45, v42
	v_sub_f32_e32 v45, v45, v49
	v_sub_f32_e32 v48, v42, v48
	v_sub_f32_e32 v42, v45, v42
	v_add_f32_e32 v41, v41, v42
	v_sub_f32_e32 v42, v48, v43
	v_add_f32_e32 v41, v42, v41
	v_add_f32_e32 v42, v46, v47
	v_add_f32_e32 v41, v49, v41
	v_sub_f32_e32 v43, v42, v46
	v_mul_f32_e32 v41, v44, v41
	v_sub_f32_e32 v43, v47, v43
	v_add_f32_e32 v41, v43, v41
	v_add_f32_e32 v43, v42, v41
	v_mul_f32_e32 v44, v43, v43
	v_fmamk_f32 v45, v44, 0x3e9b6dac, v207
	v_sub_f32_e32 v42, v43, v42
	v_fmaak_f32 v45, v44, v45, 0x3f2aaada
	v_cvt_f32_i32_e32 v46, v73
	v_sub_f32_e32 v41, v41, v42
	v_ldexp_f32 v42, v43, 1
	v_mul_f32_e32 v43, v43, v44
	v_mul_f32_e32 v43, v43, v45
	v_add_f32_e32 v44, v42, v43
	v_sub_f32_e32 v42, v44, v42
	v_mul_f32_e32 v47, 0x3f317218, v46
	v_ldexp_f32 v41, v41, 1
	v_sub_f32_e32 v42, v43, v42
	v_fma_f32 v48, v46, s8, -v47
	v_add_f32_e32 v41, v41, v42
	v_fmac_f32_e32 v48, 0xb102e308, v46
	v_add_f32_e32 v42, v44, v41
	v_add_f32_e32 v49, v47, v48
	v_sub_f32_e32 v43, v42, v44
	v_sub_f32_e32 v41, v41, v43
	v_add_f32_e32 v43, v49, v42
	v_sub_f32_e32 v44, v43, v49
	v_sub_f32_e32 v47, v49, v47
	v_sub_f32_e32 v45, v43, v44
	v_sub_f32_e32 v47, v48, v47
	v_sub_f32_e32 v45, v49, v45
	v_sub_f32_e32 v42, v42, v44
	v_add_f32_e32 v42, v42, v45
	v_add_f32_e32 v44, v47, v41
	v_sub_f32_e32 v45, v44, v47
	v_add_f32_e32 v42, v44, v42
	v_sub_f32_e32 v48, v44, v45
	v_add_f32_e32 v44, v43, v42
	v_sub_f32_e32 v47, v47, v48
	v_sub_f32_e32 v41, v41, v45
	v_sub_f32_e32 v43, v44, v43
	v_add_f32_e32 v41, v41, v47
	v_sub_f32_e32 v42, v42, v43
	v_add_f32_e32 v41, v41, v42
	s_mov_b32 s8, 0x7f800000
	v_and_b32_e32 v46, 0x7fffffff, v93
	v_add_f32_e32 v41, v44, v41
	v_cmp_neq_f32_e32 vcc, s8, v93
	s_mov_b32 s8, 0x33800000
	v_bfe_u32 v64, v17, 4, 2
	v_cndmask_b32_e32 v41, v211, v41, vcc
	v_cmp_gt_f32_e32 vcc, s8, v46
	s_waitcnt lgkmcnt(0)
	s_waitcnt lgkmcnt(0)
	s_barrier
	v_cndmask_b32_e32 v41, v41, v93, vcc
	v_sub_f32_e32 v40, v40, v41
	v_mul_f32_e32 v75, 0x4138aa3b, v40
	v_lshlrev_b32_e32 v40, 4, v64
	v_mul_u32_u24_e32 v41, 0x110, v92
	v_add3_u32 v65, 0, v40, v41
	ds_read_b128 v[40:43], v65
	ds_read_b128 v[48:51], v65 offset:64
	s_waitcnt lgkmcnt(1)
	v_mfma_f32_16x16x32_bf16 v[44:47], v[40:43], v[30:33], 0
	ds_read_b128 v[56:59], v65 offset:4416
	ds_read_b128 v[66:69], v65 offset:8768
	s_ashr_i32 s8, s14, 2
	v_mfma_f32_16x16x32_bf16 v[40:43], v[40:43], v[36:39], 0
	s_add_i32 s48, s48, s3
	s_waitcnt lgkmcnt(2)
	v_mfma_f32_16x16x32_bf16 v[44:47], v[48:51], v[22:25], v[44:47]
	v_mfma_f32_16x16x32_bf16 v[40:43], v[48:51], v[26:29], v[40:43]
	ds_read_b128 v[48:51], v65 offset:128
	s_waitcnt lgkmcnt(0)
	v_mfma_f32_16x16x32_bf16 v[44:47], v[48:51], v[10:13], v[44:47]
	v_mfma_f32_16x16x32_bf16 v[40:43], v[48:51], v[18:21], v[40:43]
	ds_read_b128 v[48:51], v65 offset:192
	s_waitcnt lgkmcnt(0)
	v_mfma_f32_16x16x32_bf16 v[52:55], v[48:51], v[2:5], v[44:47]
	v_mfma_f32_16x16x32_bf16 v[48:51], v[48:51], v[6:9], v[40:43]
	s_nop 3
	ds_read_b128 v[40:43], v65 offset:4352
	s_waitcnt lgkmcnt(0)
	v_mfma_f32_16x16x32_bf16 v[44:47], v[40:43], v[30:33], 0
	v_mfma_f32_16x16x32_bf16 v[40:43], v[40:43], v[36:39], 0
	v_mfma_f32_16x16x32_bf16 v[44:47], v[56:59], v[22:25], v[44:47]
	v_mfma_f32_16x16x32_bf16 v[40:43], v[56:59], v[26:29], v[40:43]
	ds_read_b128 v[56:59], v65 offset:4480
	s_waitcnt lgkmcnt(0)
	v_mfma_f32_16x16x32_bf16 v[44:47], v[56:59], v[10:13], v[44:47]
	v_mfma_f32_16x16x32_bf16 v[40:43], v[56:59], v[18:21], v[40:43]
	ds_read_b128 v[56:59], v65 offset:4544
	s_waitcnt lgkmcnt(0)
	v_mfma_f32_16x16x32_bf16 v[44:47], v[56:59], v[2:5], v[44:47]
	v_mfma_f32_16x16x32_bf16 v[40:43], v[56:59], v[6:9], v[40:43]
	ds_read_b128 v[56:59], v65 offset:8704
	s_waitcnt lgkmcnt(0)
	v_mfma_f32_16x16x32_bf16 v[60:63], v[56:59], v[30:33], 0
	v_mfma_f32_16x16x32_bf16 v[56:59], v[56:59], v[36:39], 0
	v_mfma_f32_16x16x32_bf16 v[60:63], v[66:69], v[22:25], v[60:63]
	v_mfma_f32_16x16x32_bf16 v[56:59], v[66:69], v[26:29], v[56:59]
	ds_read_b128 v[66:69], v65 offset:8832
	s_waitcnt lgkmcnt(0)
	v_mfma_f32_16x16x32_bf16 v[60:63], v[66:69], v[10:13], v[60:63]
	v_mfma_f32_16x16x32_bf16 v[56:59], v[66:69], v[18:21], v[56:59]
	ds_read_b128 v[66:69], v65 offset:8896
	s_waitcnt lgkmcnt(0)
	v_mfma_f32_16x16x32_bf16 v[60:63], v[66:69], v[2:5], v[60:63]
	v_mfma_f32_16x16x32_bf16 v[56:59], v[66:69], v[6:9], v[56:59]
	ds_read_b128 v[66:69], v65 offset:13056
	s_waitcnt lgkmcnt(0)
	v_mfma_f32_16x16x32_bf16 v[30:33], v[66:69], v[30:33], 0
	v_mfma_f32_16x16x32_bf16 v[36:39], v[66:69], v[36:39], 0
	ds_read_b128 v[66:69], v65 offset:13120
	s_waitcnt lgkmcnt(0)
	v_mfma_f32_16x16x32_bf16 v[22:25], v[66:69], v[22:25], v[30:33]
	s_nop 3
	ds_read_b128 v[30:33], v65 offset:13184
	s_waitcnt lgkmcnt(0)
	v_mfma_f32_16x16x32_bf16 v[10:13], v[30:33], v[10:13], v[22:25]
	s_nop 2
	ds_read_b128 v[22:25], v65 offset:13248
	v_mfma_f32_16x16x32_bf16 v[26:29], v[66:69], v[26:29], v[36:39]
	v_lshl_or_b32 v66, v64, 2, 1
	v_mfma_f32_16x16x32_bf16 v[18:21], v[30:33], v[18:21], v[26:29]
	s_waitcnt lgkmcnt(0)
	v_mfma_f32_16x16x32_bf16 v[10:13], v[22:25], v[2:5], v[10:13]
	s_nop 3
	v_and_or_b32 v26, s8, -16, v92
	s_load_dwordx2 s[8:9], s[0:1], 0x20
	v_mfma_f32_16x16x32_bf16 v[2:5], v[22:25], v[6:9], v[18:21]
	v_add_f32_e32 v7, v90, v52
	v_mul_f32_e32 v7, 0xbfb8aa3b, v7
	v_exp_f32_e32 v7, v7
	v_add_f32_e32 v8, v91, v48
	v_mul_f32_e32 v8, 0xbfb8aa3b, v8
	v_exp_f32_e32 v8, v8
	v_add_f32_e32 v7, 1.0, v7
	v_rcp_f32_e32 v7, v7
	v_lshl_add_u32 v6, v26, 2, 0
	v_add_f32_e32 v8, 1.0, v8
	v_rcp_f32_e32 v8, v8
	v_mul_f32_e32 v7, v75, v7
	v_exp_f32_e32 v65, v7
	v_mul_f32_e32 v7, 0x3fb17218, v7
	v_fmamk_f32 v9, v7, 0x3ab60b61, v208
	v_fmaak_f32 v9, v7, v9, 0x3d2aaaab
	v_fmaak_f32 v9, v7, v9, 0x3e2aaaab
	v_fma_f32 v9, v7, v9, 0.5
	v_fma_f32 v9, v7, v9, 1.0
	v_mul_f32_e64 v9, v9, -v7
	v_cmp_lt_f32_e32 vcc, s24, v7
	v_fma_f32 v7, -v65, v65, 1.0
	v_lshl_add_u32 v27, v64, 11, v6
	v_cndmask_b32_e32 v7, v7, v9, vcc
	v_max_f32_e32 v7, 0, v7
	v_sqrt_f32_e32 v7, v7
	v_lshl_add_u32 v6, v66, 9, v6
	ds_read_b32 v70, v6 offset:20480
	ds_read_b32 v38, v27 offset:46592
	v_mul_f32_e32 v67, v8, v7
	v_add_f32_e32 v7, v90, v53
	v_mul_f32_e32 v7, 0xbfb8aa3b, v7
	v_exp_f32_e32 v7, v7
	v_add_f32_e32 v6, v90, v54
	v_mul_f32_e32 v6, 0xbfb8aa3b, v6
	v_add_f32_e32 v8, v91, v49
	v_add_f32_e32 v7, 1.0, v7
	v_rcp_f32_e32 v7, v7
	v_exp_f32_e32 v6, v6
	v_mul_f32_e32 v8, 0xbfb8aa3b, v8
	v_exp_f32_e32 v8, v8
	v_mul_f32_e32 v7, v75, v7
	v_exp_f32_e32 v68, v7
	v_mul_f32_e32 v7, 0x3fb17218, v7
	v_fmamk_f32 v9, v7, 0x3ab60b61, v208
	v_fmaak_f32 v9, v7, v9, 0x3d2aaaab
	v_fmaak_f32 v9, v7, v9, 0x3e2aaaab
	v_fma_f32 v9, v7, v9, 0.5
	v_fma_f32 v9, v7, v9, 1.0
	v_mul_f32_e64 v9, v9, -v7
	v_cmp_lt_f32_e32 vcc, s24, v7
	v_fma_f32 v7, -v68, v68, 1.0
	v_add_f32_e32 v6, 1.0, v6
	v_cndmask_b32_e32 v7, v7, v9, vcc
	v_rcp_f32_e32 v6, v6
	v_add_f32_e32 v8, 1.0, v8
	v_max_f32_e32 v7, 0, v7
	v_rcp_f32_e32 v8, v8
	v_sqrt_f32_e32 v7, v7
	v_mul_f32_e32 v6, v75, v6
	v_exp_f32_e32 v71, v6
	v_mul_f32_e32 v6, 0x3fb17218, v6
	v_mul_f32_e32 v69, v8, v7
	v_fmamk_f32 v8, v6, 0x3ab60b61, v208
	v_add_f32_e32 v7, v91, v50
	v_fmaak_f32 v8, v6, v8, 0x3d2aaaab
	v_mul_f32_e32 v7, 0xbfb8aa3b, v7
	v_fmaak_f32 v8, v6, v8, 0x3e2aaaab
	v_exp_f32_e32 v7, v7
	v_fma_f32 v8, v6, v8, 0.5
	v_fma_f32 v8, v6, v8, 1.0
	v_mul_f32_e64 v8, v8, -v6
	v_cmp_lt_f32_e32 vcc, s24, v6
	v_fma_f32 v6, -v71, v71, 1.0
	v_add_f32_e32 v7, 1.0, v7
	v_cndmask_b32_e32 v6, v6, v8, vcc
	v_max_f32_e32 v6, 0, v6
	v_rcp_f32_e32 v7, v7
	v_sqrt_f32_e32 v6, v6
	v_add_f32_e32 v10, v90, v10
	v_mul_f32_e32 v10, 0xbfb8aa3b, v10
	v_exp_f32_e32 v10, v10
	v_mul_f32_e32 v73, v7, v6
	v_add_f32_e32 v6, v90, v55
	v_mul_f32_e32 v6, 0xbfb8aa3b, v6
	v_exp_f32_e32 v6, v6
	v_add_f32_e32 v7, v91, v51
	v_mul_f32_e32 v7, 0xbfb8aa3b, v7
	v_exp_f32_e32 v7, v7
	v_add_f32_e32 v6, 1.0, v6
	v_rcp_f32_e32 v6, v6
	v_add_f32_e32 v10, 1.0, v10
	v_add_f32_e32 v7, 1.0, v7
	v_rcp_f32_e32 v7, v7
	v_mul_f32_e32 v6, v75, v6
	v_exp_f32_e32 v55, v6
	v_mul_f32_e32 v6, 0x3fb17218, v6
	v_fmamk_f32 v8, v6, 0x3ab60b61, v208
	v_fmaak_f32 v8, v6, v8, 0x3d2aaaab
	v_fmaak_f32 v8, v6, v8, 0x3e2aaaab
	v_fma_f32 v8, v6, v8, 0.5
	v_fma_f32 v8, v6, v8, 1.0
	v_mul_f32_e64 v8, v8, -v6
	v_cmp_lt_f32_e32 vcc, s24, v6
	v_fma_f32 v6, -v55, v55, 1.0
	v_rcp_f32_e32 v10, v10
	v_cndmask_b32_e32 v6, v6, v8, vcc
	v_max_f32_e32 v6, 0, v6
	v_sqrt_f32_e32 v6, v6
	v_mul_f32_e32 v10, v75, v10
	v_add_f32_e32 v2, v91, v2
	v_mul_f32_e32 v2, 0xbfb8aa3b, v2
	v_mul_f32_e32 v74, v7, v6
	v_add_f32_e32 v6, v90, v44
	v_mul_f32_e32 v6, 0xbfb8aa3b, v6
	v_exp_f32_e32 v6, v6
	v_add_f32_e32 v7, v91, v40
	v_mul_f32_e32 v7, 0xbfb8aa3b, v7
	v_exp_f32_e32 v7, v7
	v_add_f32_e32 v6, 1.0, v6
	v_rcp_f32_e32 v6, v6
	v_exp_f32_e32 v2, v2
	v_add_f32_e32 v7, 1.0, v7
	v_rcp_f32_e32 v7, v7
	v_mul_f32_e32 v6, v75, v6
	v_exp_f32_e32 v48, v6
	v_mul_f32_e32 v6, 0x3fb17218, v6
	v_fmamk_f32 v8, v6, 0x3ab60b61, v208
	v_fmaak_f32 v8, v6, v8, 0x3d2aaaab
	v_fmaak_f32 v8, v6, v8, 0x3e2aaaab
	v_fma_f32 v8, v6, v8, 0.5
	v_fma_f32 v8, v6, v8, 1.0
	v_mul_f32_e64 v8, v8, -v6
	v_cmp_lt_f32_e32 vcc, s24, v6
	v_fma_f32 v6, -v48, v48, 1.0
	v_add_f32_e32 v2, 1.0, v2
	v_cndmask_b32_e32 v6, v6, v8, vcc
	v_max_f32_e32 v6, 0, v6
	v_sqrt_f32_e32 v6, v6
	v_rcp_f32_e32 v2, v2
	v_add_f32_e32 v4, v91, v4
	v_mul_f32_e32 v4, 0xbfb8aa3b, v4
	v_mul_f32_e32 v49, v7, v6
	v_add_f32_e32 v6, v90, v45
	v_mul_f32_e32 v6, 0xbfb8aa3b, v6
	v_exp_f32_e32 v6, v6
	v_add_f32_e32 v7, v91, v41
	v_mul_f32_e32 v7, 0xbfb8aa3b, v7
	v_exp_f32_e32 v7, v7
	v_add_f32_e32 v6, 1.0, v6
	v_rcp_f32_e32 v6, v6
	v_exp_f32_e32 v4, v4
	v_add_f32_e32 v7, 1.0, v7
	v_rcp_f32_e32 v7, v7
	v_mul_f32_e32 v6, v75, v6
	v_exp_f32_e32 v50, v6
	v_mul_f32_e32 v6, 0x3fb17218, v6
	v_fmamk_f32 v8, v6, 0x3ab60b61, v208
	v_fmaak_f32 v8, v6, v8, 0x3d2aaaab
	v_fmaak_f32 v8, v6, v8, 0x3e2aaaab
	v_fma_f32 v8, v6, v8, 0.5
	v_fma_f32 v8, v6, v8, 1.0
	v_mul_f32_e64 v8, v8, -v6
	v_cmp_lt_f32_e32 vcc, s24, v6
	v_fma_f32 v6, -v50, v50, 1.0
	v_add_f32_e32 v4, 1.0, v4
	v_cndmask_b32_e32 v6, v6, v8, vcc
	v_max_f32_e32 v6, 0, v6
	v_sqrt_f32_e32 v6, v6
	v_rcp_f32_e32 v4, v4
	v_add_f32_e32 v5, v91, v5
	v_mul_f32_e32 v5, 0xbfb8aa3b, v5
	v_mul_f32_e32 v52, v7, v6
	v_add_f32_e32 v6, v90, v46
	v_mul_f32_e32 v6, 0xbfb8aa3b, v6
	v_exp_f32_e32 v6, v6
	v_add_f32_e32 v7, v91, v42
	v_mul_f32_e32 v7, 0xbfb8aa3b, v7
	v_exp_f32_e32 v7, v7
	v_add_f32_e32 v6, 1.0, v6
	v_rcp_f32_e32 v6, v6
	v_exp_f32_e32 v5, v5
	v_add_f32_e32 v7, 1.0, v7
	v_rcp_f32_e32 v7, v7
	v_mul_f32_e32 v6, v75, v6
	v_exp_f32_e32 v51, v6
	v_mul_f32_e32 v6, 0x3fb17218, v6
	v_fmamk_f32 v8, v6, 0x3ab60b61, v208
	v_fmaak_f32 v8, v6, v8, 0x3d2aaaab
	v_fmaak_f32 v8, v6, v8, 0x3e2aaaab
	v_fma_f32 v8, v6, v8, 0.5
	v_fma_f32 v8, v6, v8, 1.0
	v_mul_f32_e64 v8, v8, -v6
	v_cmp_lt_f32_e32 vcc, s24, v6
	v_fma_f32 v6, -v51, v51, 1.0
	v_add_f32_e32 v3, v91, v3
	v_cndmask_b32_e32 v6, v6, v8, vcc
	v_max_f32_e32 v6, 0, v6
	v_sqrt_f32_e32 v6, v6
	v_mul_f32_e32 v3, 0xbfb8aa3b, v3
	v_exp_f32_e32 v3, v3
	v_add_f32_e32 v5, 1.0, v5
	v_mul_f32_e32 v53, v7, v6
	v_add_f32_e32 v6, v90, v47
	v_mul_f32_e32 v6, 0xbfb8aa3b, v6
	v_exp_f32_e32 v6, v6
	v_add_f32_e32 v7, v91, v43
	v_mul_f32_e32 v7, 0xbfb8aa3b, v7
	v_exp_f32_e32 v7, v7
	v_add_f32_e32 v6, 1.0, v6
	v_rcp_f32_e32 v6, v6
	v_rcp_f32_e32 v5, v5
	v_add_f32_e32 v7, 1.0, v7
	v_rcp_f32_e32 v7, v7
	v_mul_f32_e32 v6, v75, v6
	v_exp_f32_e32 v47, v6
	v_mul_f32_e32 v6, 0x3fb17218, v6
	v_fmamk_f32 v8, v6, 0x3ab60b61, v208
	v_fmaak_f32 v8, v6, v8, 0x3d2aaaab
	v_fmaak_f32 v8, v6, v8, 0x3e2aaaab
	v_fma_f32 v8, v6, v8, 0.5
	v_fma_f32 v8, v6, v8, 1.0
	v_mul_f32_e64 v8, v8, -v6
	v_cmp_lt_f32_e32 vcc, s24, v6
	v_fma_f32 v6, -v47, v47, 1.0
	v_add_f32_e32 v3, 1.0, v3
	v_cndmask_b32_e32 v6, v6, v8, vcc
	v_max_f32_e32 v6, 0, v6
	v_sqrt_f32_e32 v6, v6
	v_rcp_f32_e32 v3, v3
	ds_read2st64_b32 v[24:25], v27 offset0:80 offset1:84
	ds_read2st64_b32 v[20:21], v27 offset0:86 offset1:112
	v_mul_f32_e32 v54, v7, v6
	v_add_f32_e32 v6, v90, v60
	v_mul_f32_e32 v6, 0xbfb8aa3b, v6
	v_exp_f32_e32 v6, v6
	v_add_f32_e32 v7, v91, v56
	v_mul_f32_e32 v7, 0xbfb8aa3b, v7
	v_exp_f32_e32 v7, v7
	v_add_f32_e32 v6, 1.0, v6
	v_rcp_f32_e32 v6, v6
	ds_read2st64_b32 v[22:23], v27 offset0:114 offset1:116
	v_add_f32_e32 v7, 1.0, v7
	v_rcp_f32_e32 v7, v7
	v_mul_f32_e32 v6, v75, v6
	v_exp_f32_e32 v39, v6
	v_mul_f32_e32 v6, 0x3fb17218, v6
	v_fmamk_f32 v18, v6, 0x3ab60b61, v208
	v_fmaak_f32 v18, v6, v18, 0x3d2aaaab
	v_fmaak_f32 v18, v6, v18, 0x3e2aaaab
	v_fma_f32 v18, v6, v18, 0.5
	v_fma_f32 v18, v6, v18, 1.0
	v_mul_f32_e64 v18, v18, -v6
	v_cmp_lt_f32_e32 vcc, s24, v6
	v_fma_f32 v6, -v39, v39, 1.0
	ds_read2st64_b32 v[8:9], v27 offset0:118 offset1:144
	v_cndmask_b32_e32 v6, v6, v18, vcc
	v_max_f32_e32 v6, 0, v6
	v_sqrt_f32_e32 v6, v6
	s_nop 0
	v_mul_f32_e32 v41, v7, v6
	v_add_f32_e32 v6, v90, v61
	v_mul_f32_e32 v6, 0xbfb8aa3b, v6
	v_exp_f32_e32 v6, v6
	v_add_f32_e32 v7, v91, v57
	v_mul_f32_e32 v7, 0xbfb8aa3b, v7
	v_exp_f32_e32 v7, v7
	v_add_f32_e32 v6, 1.0, v6
	v_rcp_f32_e32 v6, v6
	v_add_f32_e32 v7, 1.0, v7
	v_rcp_f32_e32 v7, v7
	v_mul_f32_e32 v6, v75, v6
	v_exp_f32_e32 v40, v6
	v_mul_f32_e32 v6, 0x3fb17218, v6
	v_fmamk_f32 v18, v6, 0x3ab60b61, v208
	v_fmaak_f32 v18, v6, v18, 0x3d2aaaab
	v_fmaak_f32 v18, v6, v18, 0x3e2aaaab
	v_fma_f32 v18, v6, v18, 0.5
	v_fma_f32 v18, v6, v18, 1.0
	v_mul_f32_e64 v18, v18, -v6
	v_cmp_lt_f32_e32 vcc, s24, v6
	v_fma_f32 v6, -v40, v40, 1.0
	s_nop 0
	v_cndmask_b32_e32 v6, v6, v18, vcc
	v_max_f32_e32 v6, 0, v6
	v_sqrt_f32_e32 v6, v6
	ds_read2st64_b32 v[18:19], v27 offset0:146 offset1:148
	v_mul_f32_e32 v43, v7, v6
	v_add_f32_e32 v6, v90, v62
	v_mul_f32_e32 v6, 0xbfb8aa3b, v6
	v_exp_f32_e32 v6, v6
	v_add_f32_e32 v7, v91, v58
	v_mul_f32_e32 v7, 0xbfb8aa3b, v7
	v_exp_f32_e32 v7, v7
	v_add_f32_e32 v6, 1.0, v6
	v_rcp_f32_e32 v6, v6
	v_lshl_add_u32 v58, v26, 1, 0
	v_add_f32_e32 v7, 1.0, v7
	v_rcp_f32_e32 v7, v7
	v_mul_f32_e32 v6, v75, v6
	v_exp_f32_e32 v42, v6
	v_mul_f32_e32 v6, 0x3fb17218, v6
	v_fmamk_f32 v28, v6, 0x3ab60b61, v208
	v_fmaak_f32 v28, v6, v28, 0x3d2aaaab
	v_fmaak_f32 v28, v6, v28, 0x3e2aaaab
	v_fma_f32 v28, v6, v28, 0.5
	v_fma_f32 v28, v6, v28, 1.0
	v_mul_f32_e64 v28, v28, -v6
	v_cmp_lt_f32_e32 vcc, s24, v6
	v_fma_f32 v6, -v42, v42, 1.0
	s_nop 0
	v_cndmask_b32_e32 v6, v6, v28, vcc
	v_max_f32_e32 v6, 0, v6
	v_sqrt_f32_e32 v6, v6
	s_nop 0
	v_mul_f32_e32 v45, v7, v6
	v_add_f32_e32 v6, v90, v63
	v_mul_f32_e32 v6, 0xbfb8aa3b, v6
	v_exp_f32_e32 v6, v6
	v_add_f32_e32 v7, v91, v59
	v_mul_f32_e32 v7, 0xbfb8aa3b, v7
	v_exp_f32_e32 v7, v7
	v_add_f32_e32 v6, 1.0, v6
	v_rcp_f32_e32 v6, v6
	v_add_f32_e32 v7, 1.0, v7
	v_rcp_f32_e32 v7, v7
	v_mul_f32_e32 v6, v75, v6
	v_exp_f32_e32 v44, v6
	v_mul_f32_e32 v6, 0x3fb17218, v6
	v_fmamk_f32 v28, v6, 0x3ab60b61, v208
	v_fmaak_f32 v28, v6, v28, 0x3d2aaaab
	v_fmaak_f32 v28, v6, v28, 0x3e2aaaab
	v_fma_f32 v28, v6, v28, 0.5
	v_fma_f32 v28, v6, v28, 1.0
	v_mul_f32_e64 v28, v28, -v6
	v_cmp_lt_f32_e32 vcc, s24, v6
	v_fma_f32 v6, -v44, v44, 1.0
	s_nop 0
	v_cndmask_b32_e32 v6, v6, v28, vcc
	v_exp_f32_e32 v28, v10
	v_mul_f32_e32 v10, 0x3fb17218, v10
	v_fmamk_f32 v29, v10, 0x3ab60b61, v208
	v_fmaak_f32 v29, v10, v29, 0x3d2aaaab
	v_fmaak_f32 v29, v10, v29, 0x3e2aaaab
	v_fma_f32 v29, v10, v29, 0.5
	v_fma_f32 v29, v10, v29, 1.0
	v_mul_f32_e64 v29, v29, -v10
	v_cmp_lt_f32_e32 vcc, s24, v10
	v_fma_f32 v10, -v28, v28, 1.0
	v_max_f32_e32 v6, 0, v6
	v_cndmask_b32_e32 v10, v10, v29, vcc
	v_max_f32_e32 v10, 0, v10
	v_sqrt_f32_e32 v10, v10
	v_sqrt_f32_e32 v6, v6
	v_mul_f32_e32 v29, v2, v10
	v_add_f32_e32 v2, v90, v11
	v_mul_f32_e32 v2, 0xbfb8aa3b, v2
	v_exp_f32_e32 v2, v2
	v_mul_f32_e32 v46, v7, v6
	ds_read2st64_b32 v[6:7], v27 offset0:150 offset1:176
	v_add_f32_e32 v2, 1.0, v2
	v_rcp_f32_e32 v2, v2
	s_nop 0
	v_mul_f32_e32 v2, v75, v2
	v_exp_f32_e32 v30, v2
	v_mul_f32_e32 v2, 0x3fb17218, v2
	v_fmamk_f32 v10, v2, 0x3ab60b61, v208
	v_fmaak_f32 v10, v2, v10, 0x3d2aaaab
	v_fmaak_f32 v10, v2, v10, 0x3e2aaaab
	v_fma_f32 v10, v2, v10, 0.5
	v_fma_f32 v10, v2, v10, 1.0
	v_mul_f32_e64 v10, v10, -v2
	v_cmp_lt_f32_e32 vcc, s24, v2
	v_fma_f32 v2, -v30, v30, 1.0
	s_nop 0
	v_cndmask_b32_e32 v2, v2, v10, vcc
	v_add_f32_e32 v10, v90, v12
	v_mul_f32_e32 v10, 0xbfb8aa3b, v10
	v_exp_f32_e32 v10, v10
	v_max_f32_e32 v2, 0, v2
	v_sqrt_f32_e32 v2, v2
	v_or_b32_e32 v12, s13, v64
	v_add_f32_e32 v10, 1.0, v10
	v_rcp_f32_e32 v10, v10
	v_mul_f32_e32 v31, v3, v2
	ds_read2st64_b32 v[2:3], v27 offset0:178 offset1:180
	s_movk_i32 s13, 0x110
	v_mul_f32_e32 v10, v75, v10
	v_exp_f32_e32 v32, v10
	v_mul_f32_e32 v10, 0x3fb17218, v10
	v_fmamk_f32 v11, v10, 0x3ab60b61, v208
	v_fmaak_f32 v11, v10, v11, 0x3d2aaaab
	v_fmaak_f32 v11, v10, v11, 0x3e2aaaab
	v_fma_f32 v11, v10, v11, 0.5
	v_fma_f32 v11, v10, v11, 1.0
	v_mul_f32_e64 v11, v11, -v10
	v_cmp_lt_f32_e32 vcc, s24, v10
	v_fma_f32 v10, -v32, v32, 1.0
	s_nop 0
	v_cndmask_b32_e32 v10, v10, v11, vcc
	v_max_f32_e32 v10, 0, v10
	v_sqrt_f32_e32 v10, v10
	s_nop 0
	v_mul_f32_e32 v33, v4, v10
	v_add_f32_e32 v4, v90, v13
	v_mul_f32_e32 v4, 0xbfb8aa3b, v4
	v_exp_f32_e32 v4, v4
	v_ashrrev_i32_e32 v13, 31, v12
	v_add_f32_e32 v4, 1.0, v4
	v_rcp_f32_e32 v4, v4
	s_nop 0
	v_mul_f32_e32 v4, v75, v4
	v_exp_f32_e32 v36, v4
	v_mul_f32_e32 v4, 0x3fb17218, v4
	v_fmamk_f32 v10, v4, 0x3ab60b61, v208
	v_fmaak_f32 v10, v4, v10, 0x3d2aaaab
	v_fmaak_f32 v10, v4, v10, 0x3e2aaaab
	v_fma_f32 v10, v4, v10, 0.5
	v_fma_f32 v10, v4, v10, 1.0
	v_mul_f32_e64 v10, v10, -v4
	v_cmp_lt_f32_e32 vcc, s24, v4
	v_fma_f32 v4, -v36, v36, 1.0
	s_nop 0
	v_cndmask_b32_e32 v4, v4, v10, vcc
	v_max_f32_e32 v4, 0, v4
	v_sqrt_f32_e32 v4, v4
	s_nop 0
	v_mul_f32_e32 v37, v5, v4
	v_add_u32_e32 v4, s20, v26
	v_ashrrev_i32_e32 v5, 31, v4
	v_lshlrev_b64 v[4:5], 2, v[4:5]
	s_waitcnt lgkmcnt(0)
	v_lshl_add_u64 v[10:11], s[8:9], 0, v[4:5]
	v_lshlrev_b64 v[26:27], 13, v[12:13]
	v_lshl_add_u64 v[56:57], v[10:11], 0, v[26:27]
	global_load_dword v13, v[56:57], off
	v_or_b32_e32 v124, 4, v12
	v_ashrrev_i32_e32 v125, 31, v124
	v_lshlrev_b64 v[124:125], 13, v[124:125]
	v_lshl_add_u64 v[124:125], v[10:11], 0, v[124:125]
	global_load_dword v120, v[124:125], off
	v_or_b32_e32 v126, 8, v12
	v_ashrrev_i32_e32 v127, 31, v126
	v_lshlrev_b64 v[126:127], 13, v[126:127]
	v_lshl_add_u64 v[126:127], v[10:11], 0, v[126:127]
	global_load_dword v121, v[126:127], off
	v_or_b32_e32 v128, 12, v12
	v_ashrrev_i32_e32 v129, 31, v128
	v_lshlrev_b64 v[128:129], 13, v[128:129]
	v_lshl_add_u64 v[128:129], v[10:11], 0, v[128:129]
	global_load_dword v122, v[128:129], off
	s_movk_i32 s8, 0x440
	v_mad_u32_u24 v56, v64, s8, v58
	s_mov_b32 s8, 0x54a0000
	s_waitcnt vmcnt(3)
	v_mul_f32_e32 v13, v65, v13
	v_fmac_f32_e32 v13, v67, v24
	v_bfe_u32 v24, v13, 16, 1
	v_add3_u32 v24, v13, v24, s69
	ds_write_b16_d16_hi v56, v24 offset:53248
	v_mul_f32_e32 v24, v68, v13
	v_fmac_f32_e32 v24, v69, v70
	v_bfe_u32 v13, v24, 16, 1
	v_add3_u32 v56, v24, v13, s69
	v_mul_f32_e32 v24, v71, v24
	v_fmac_f32_e32 v24, v73, v25
	v_bfe_u32 v25, v24, 16, 1
	v_mad_u32_u24 v13, v66, s13, v58
	v_add3_u32 v25, v24, v25, s69
	ds_write_b16_d16_hi v13, v25 offset:53520
	v_mul_f32_e32 v55, v55, v24
	v_lshl_add_u64 v[24:25], s[44:45], 0, v[26:27]
	v_lshl_add_u64 v[24:25], v[24:25], 0, v[4:5]
	v_add_co_u32_e32 v24, vcc, s8, v24
	v_fmac_f32_e32 v55, v74, v20
	s_nop 0
	v_addc_co_u32_e32 v25, vcc, 0, v25, vcc
	global_store_dword v[24:25], v55, off
	v_or_b32_e32 v24, 4, v12
	v_ashrrev_i32_e32 v25, 31, v24
	v_bfe_u32 v20, v55, 16, 1
	v_lshlrev_b64 v[24:25], 13, v[24:25]
	v_add3_u32 v20, v55, v20, s69
	v_lshl_add_u64 v[26:27], v[10:11], 0, v[24:25]
	ds_write_b16_d16_hi v13, v20 offset:53792
	v_add_u32_e32 v26, 0xff0, v13
	ds_write_b16_d16_hi v13, v56 offset:53248
	s_waitcnt vmcnt(3)
	v_mov_b32_e32 v20, v120
	v_mul_f32_e32 v20, v48, v20
	v_fmac_f32_e32 v20, v49, v21
	v_bfe_u32 v21, v20, 16, 1
	v_add3_u32 v21, v20, v21, s69
	v_mul_f32_e32 v20, v50, v20
	v_fmac_f32_e32 v20, v52, v22
	ds_write_b16_d16_hi v13, v21 offset:57328
	v_bfe_u32 v21, v20, 16, 1
	v_add3_u32 v21, v20, v21, s69
	v_mul_f32_e32 v20, v51, v20
	v_fmac_f32_e32 v20, v53, v23
	ds_write_b16_d16_hi v13, v21 offset:57600
	v_bfe_u32 v21, v20, 16, 1
	v_add3_u32 v21, v20, v21, s69
	ds_write_b16_d16_hi v13, v21 offset:57872
	v_mul_f32_e32 v22, v47, v20
	v_lshl_add_u64 v[20:21], s[44:45], 0, v[24:25]
	v_lshl_add_u64 v[20:21], v[20:21], 0, v[4:5]
	v_add_co_u32_e32 v20, vcc, s8, v20
	v_fmac_f32_e32 v22, v54, v8
	s_nop 0
	v_addc_co_u32_e32 v21, vcc, 0, v21, vcc
	global_store_dword v[20:21], v22, off
	v_or_b32_e32 v20, 8, v12
	v_ashrrev_i32_e32 v21, 31, v20
	v_bfe_u32 v8, v22, 16, 1
	v_lshlrev_b64 v[20:21], 13, v[20:21]
	v_add3_u32 v8, v22, v8, s69
	v_lshl_add_u64 v[22:23], v[10:11], 0, v[20:21]
	ds_write_b16_d16_hi v13, v8 offset:58144
	s_waitcnt vmcnt(3)
	v_mov_b32_e32 v8, v121
	v_mul_f32_e32 v8, v39, v8
	v_fmac_f32_e32 v8, v9, v41
	v_bfe_u32 v9, v8, 16, 1
	v_add3_u32 v9, v8, v9, s69
	v_mul_f32_e32 v8, v40, v8
	v_fmac_f32_e32 v8, v18, v43
	ds_write_b16_d16_hi v13, v9 offset:61680
	v_bfe_u32 v9, v8, 16, 1
	v_add3_u32 v9, v8, v9, s69
	v_mul_f32_e32 v8, v42, v8
	v_fmac_f32_e32 v8, v45, v19
	ds_write_b16_d16_hi v13, v9 offset:61952
	v_bfe_u32 v9, v8, 16, 1
	v_add3_u32 v9, v8, v9, s69
	ds_write_b16_d16_hi v13, v9 offset:62224
	v_mul_f32_e32 v18, v44, v8
	v_lshl_add_u64 v[8:9], s[44:45], 0, v[20:21]
	v_lshl_add_u64 v[8:9], v[8:9], 0, v[4:5]
	v_add_co_u32_e32 v8, vcc, s8, v8
	v_fmac_f32_e32 v18, v46, v6
	s_nop 0
	v_addc_co_u32_e32 v9, vcc, 0, v9, vcc
	global_store_dword v[8:9], v18, off
	v_or_b32_e32 v8, 12, v12
	v_ashrrev_i32_e32 v9, 31, v8
	v_bfe_u32 v6, v18, 16, 1
	v_lshlrev_b64 v[8:9], 13, v[8:9]
	v_add3_u32 v6, v18, v6, s69
	v_lshl_add_u64 v[10:11], v[10:11], 0, v[8:9]
	ds_write_b16_d16_hi v13, v6 offset:62496
	v_add_u32_e32 v10, 0x101f0, v13
	v_add_u32_e32 v11, s12, v72
	v_mov_b64_e32 v[12:13], s[64:65]
	s_waitcnt vmcnt(3)
	v_mov_b32_e32 v6, v122
	v_mul_f32_e32 v6, v28, v6
	v_fmac_f32_e32 v6, v7, v29
	v_bfe_u32 v7, v6, 16, 1
	v_add3_u32 v7, v6, v7, s69
	v_mul_f32_e32 v6, v30, v6
	v_fmac_f32_e32 v6, v2, v31
	v_bfe_u32 v2, v6, 16, 1
	v_add3_u32 v2, v6, v2, s69
	ds_write_b16_d16_hi v26, v2 offset:62224
	v_mul_f32_e32 v2, v32, v6
	v_fmac_f32_e32 v2, v3, v33
	v_mul_f32_e32 v6, v36, v2
	v_bfe_u32 v3, v2, 16, 1
	v_fmac_f32_e32 v6, v38, v37
	v_add3_u32 v3, v2, v3, s69
	v_bfe_u32 v2, v6, 16, 1
	v_add3_u32 v2, v6, v2, s69
	ds_write_b16_d16_hi v10, v7
	ds_write_b16_d16_hi v26, v3 offset:62496
	ds_write_b16_d16_hi v26, v2 offset:62768
	v_lshl_add_u64 v[2:3], s[44:45], 0, v[8:9]
	v_lshl_add_u64 v[2:3], v[2:3], 0, v[4:5]
	v_add_co_u32_e32 v2, vcc, s8, v2
	v_add_u32_e32 v10, 0, v34
	s_nop 0
	v_addc_co_u32_e32 v3, vcc, 0, v3, vcc
	global_store_dword v[2:3], v6, off
	v_mad_i64_i32 v[6:7], s[8:9], v11, s68, v[12:13]
	v_lshl_add_u64 v[6:7], v[6:7], 0, v[14:15]
	v_lshl_add_u64 v[6:7], v[6:7], 0, v[34:35]
	v_add_co_u32_e32 v6, vcc, s15, v6
	s_waitcnt lgkmcnt(0)
	s_waitcnt lgkmcnt(0)
	s_nop 0
	v_addc_co_u32_e32 v7, vcc, 0, v7, vcc
	s_barrier
	global_load_dwordx4 v[6:9], v[6:7], off
	v_mad_u64_u32 v[2:3], s[8:9], v72, s13, v[10:11]
	ds_read_b128 v[2:5], v2 offset:53248
	s_waitcnt lgkmcnt(0)
	v_lshlrev_b32_e32 v19, 16, v3
	v_lshlrev_b32_e32 v18, 16, v2
	v_and_b32_e32 v3, 0xffff0000, v3
	v_and_b32_e32 v2, 0xffff0000, v2
	s_waitcnt vmcnt(0)
	v_lshlrev_b32_e32 v21, 16, v7
	v_lshlrev_b32_e32 v20, 16, v6
	v_and_b32_e32 v7, 0xffff0000, v7
	v_and_b32_e32 v6, 0xffff0000, v6
	v_pk_mul_f32 v[18:19], v[18:19], v[20:21]
	v_pk_mul_f32 v[2:3], v[2:3], v[6:7]
	v_lshlrev_b32_e32 v7, 16, v5
	v_lshlrev_b32_e32 v6, 16, v4
	v_lshlrev_b32_e32 v21, 16, v9
	v_lshlrev_b32_e32 v20, 16, v8
	v_and_b32_e32 v5, 0xffff0000, v5
	v_and_b32_e32 v4, 0xffff0000, v4
	v_and_b32_e32 v9, 0xffff0000, v9
	v_and_b32_e32 v8, 0xffff0000, v8
	v_pk_mul_f32 v[6:7], v[6:7], v[20:21]
	v_pk_mul_f32 v[4:5], v[4:5], v[8:9]
	v_bfe_u32 v20, v3, 16, 1
	v_bfe_u32 v21, v2, 16, 1
	v_bfe_u32 v8, v5, 16, 1
	v_bfe_u32 v9, v4, 16, 1
	v_add3_u32 v2, v2, v21, s69
	v_add3_u32 v3, v3, v20, s69
	v_bfe_u32 v20, v6, 16, 1
	v_bfe_u32 v21, v7, 16, 1
	v_add3_u32 v4, v4, v9, s69
	v_add3_u32 v5, v5, v8, s69
	v_bfe_u32 v8, v18, 16, 1
	v_bfe_u32 v9, v19, 16, 1
	v_add3_u32 v7, v7, v21, s69
	v_add3_u32 v6, v6, v20, s69
	v_add3_u32 v9, v19, v9, s69
	v_add3_u32 v8, v18, v8, s69
	v_lshrrev_b32_e32 v6, 16, v6
	v_lshrrev_b32_e32 v7, 16, v7
	v_mov_b64_e32 v[18:19], s[28:29]
	v_and_or_b32 v5, v5, s7, v7
	v_and_or_b32 v4, v4, s7, v6
	v_mad_i64_i32 v[6:7], s[8:9], v11, s18, v[18:19]
	v_lshrrev_b32_e32 v8, 16, v8
	v_lshrrev_b32_e32 v9, 16, v9
	v_lshl_add_u64 v[6:7], v[6:7], 0, v[14:15]
	v_and_or_b32 v3, v3, s7, v9
	v_and_or_b32 v2, v2, s7, v8
	v_lshl_add_u64 v[6:7], v[6:7], 0, v[34:35]
	global_store_dwordx4 v[6:7], v[2:5], off offset:2048
	s_nop 1
	v_add_u32_e32 v2, 0x200, v17
	v_ashrrev_i32_e32 v2, 4, v2
	v_add_u32_e32 v17, s12, v2
	v_mad_i64_i32 v[6:7], s[8:9], v17, s68, v[12:13]
	v_lshl_add_u64 v[6:7], v[6:7], 0, v[14:15]
	v_lshl_add_u64 v[6:7], v[6:7], 0, v[34:35]
	v_add_co_u32_e32 v6, vcc, s15, v6
	v_mad_u64_u32 v[2:3], s[8:9], v2, s13, v[10:11]
	s_nop 0
	v_addc_co_u32_e32 v7, vcc, 0, v7, vcc
	global_load_dwordx4 v[6:9], v[6:7], off
	ds_read_b128 v[2:5], v2 offset:53248
	s_waitcnt lgkmcnt(0)
	v_lshlrev_b32_e32 v11, 16, v3
	v_lshlrev_b32_e32 v10, 16, v2
	v_and_b32_e32 v3, 0xffff0000, v3
	v_and_b32_e32 v2, 0xffff0000, v2
	s_waitcnt vmcnt(0)
	v_lshlrev_b32_e32 v13, 16, v7
	v_lshlrev_b32_e32 v12, 16, v6
	v_and_b32_e32 v7, 0xffff0000, v7
	v_and_b32_e32 v6, 0xffff0000, v6
	v_pk_mul_f32 v[10:11], v[10:11], v[12:13]
	v_pk_mul_f32 v[2:3], v[2:3], v[6:7]
	v_lshlrev_b32_e32 v7, 16, v5
	v_lshlrev_b32_e32 v6, 16, v4
	v_lshlrev_b32_e32 v13, 16, v9
	v_lshlrev_b32_e32 v12, 16, v8
	v_pk_mul_f32 v[6:7], v[6:7], v[12:13]
	v_and_b32_e32 v5, 0xffff0000, v5
	v_and_b32_e32 v4, 0xffff0000, v4
	v_and_b32_e32 v9, 0xffff0000, v9
	v_and_b32_e32 v8, 0xffff0000, v8
	v_bfe_u32 v12, v3, 16, 1
	v_bfe_u32 v13, v2, 16, 1
	v_pk_mul_f32 v[4:5], v[4:5], v[8:9]
	v_add3_u32 v2, v2, v13, s69
	v_add3_u32 v3, v3, v12, s69
	v_bfe_u32 v12, v6, 16, 1
	v_bfe_u32 v13, v7, 16, 1
	v_bfe_u32 v8, v5, 16, 1
	v_bfe_u32 v9, v4, 16, 1
	v_add3_u32 v7, v7, v13, s69
	v_add3_u32 v6, v6, v12, s69
	v_add3_u32 v4, v4, v9, s69
	v_add3_u32 v5, v5, v8, s69
	v_lshrrev_b32_e32 v6, 16, v6
	v_lshrrev_b32_e32 v7, 16, v7
	v_bfe_u32 v8, v10, 16, 1
	v_bfe_u32 v9, v11, 16, 1
	v_and_or_b32 v5, v5, s7, v7
	v_and_or_b32 v4, v4, s7, v6
	v_mad_i64_i32 v[6:7], s[8:9], v17, s18, v[18:19]
	v_add3_u32 v9, v11, v9, s69
	v_add3_u32 v8, v10, v8, s69
	v_readlane_b32 s8, v252, 21
	v_lshrrev_b32_e32 v8, 16, v8
	v_lshrrev_b32_e32 v9, 16, v9
	v_lshl_add_u64 v[6:7], v[6:7], 0, v[14:15]
	s_add_i32 s47, s47, s8
	v_and_or_b32 v3, v3, s7, v9
	v_and_or_b32 v2, v2, s7, v8
	v_lshl_add_u64 v[6:7], v[6:7], 0, v[34:35]
	s_cmpk_gt_i32 s48, 0x7f
	global_store_dwordx4 v[6:7], v[2:5], off offset:2048
	s_cbranch_scc1 .LBB0_684
